# v60 plus lever 1: FF1 epilogue vmcnt(0) removed (bias already in registers; next-tile prefetched DMA loads stay covered by the next tile's first counted wait)
# baseline (speedup 1.0000x reference)
.LBB0_584:
	v_lshl_or_b32 v162, s77, 8, v167
	v_ashrrev_i32_e32 v163, 31, v162
	v_lshl_add_u64 v[130:131], v[162:163], 2, s[42:43]
	v_lshl_add_u32 v164, s40, 8, v1
	v_ashrrev_i32_e32 v165, 31, v164
	v_or_b32_e32 v172, 16, v164
	v_lshlrev_b64 v[174:175], 13, v[164:165]
	v_lshlrev_b64 v[176:177], 1, v[162:163]
	v_ashrrev_i32_e32 v173, 31, v172
	v_lshl_add_u64 v[162:163], s[68:69], 0, v[174:175]
	v_lshlrev_b64 v[172:173], 13, v[172:173]
	v_lshl_add_u64 v[162:163], v[162:163], 0, v[176:177]
	v_lshl_add_u64 v[172:173], s[68:69], 0, v[172:173]
	v_lshl_add_u64 v[172:173], v[172:173], 0, v[176:177]
	s_mov_b64 s[4:5], -1
	v_mov_b32_e32 v142, v226
	v_mov_b32_e32 v143, v227
	v_mov_b32_e32 v144, v228
	v_mov_b32_e32 v145, v229
	v_mov_b32_e32 v138, v230
	v_mov_b32_e32 v139, v231
	v_mov_b32_e32 v140, v232
	v_mov_b32_e32 v141, v233
	v_mov_b32_e32 v134, v234
	v_mov_b32_e32 v135, v235
	v_mov_b32_e32 v136, v236
	v_mov_b32_e32 v137, v237
	v_mov_b32_e32 v130, v238
	v_mov_b32_e32 v131, v239
	v_mov_b32_e32 v132, v240
	v_mov_b32_e32 v133, v241
	v_pk_add_f32 v[126:127], v[126:127], v[142:143]
	v_pk_add_f32 v[128:129], v[128:129], v[144:145]
	v_pk_add_f32 v[124:125], v[124:125], v[140:141]
	v_pk_add_f32 v[106:107], v[106:107], v[130:131]
	v_pk_add_f32 v[122:123], v[122:123], v[138:139]
	v_pk_add_f32 v[110:111], v[110:111], v[134:135]
	v_pk_add_f32 v[108:109], v[108:109], v[132:133]
	v_max_f32_e32 v126, 0, v126
	v_max_f32_e32 v127, 0, v127
	v_max_f32_e32 v106, 0, v106
	v_pk_add_f32 v[112:113], v[112:113], v[136:137]
	v_pk_add_f32 v[118:119], v[118:119], v[142:143]
	v_max_f32_e32 v122, 0, v122
	v_max_f32_e32 v123, 0, v123
	v_max_f32_e32 v128, 0, v128
	v_max_f32_e32 v124, 0, v124
	v_max_f32_e32 v129, 0, v129
	v_max_f32_e32 v125, 0, v125
	v_max_f32_e32 v110, 0, v110
	v_max_f32_e32 v111, 0, v111
	v_max_f32_e32 v107, 0, v107
	v_max_f32_e32 v108, 0, v108
	v_max_f32_e32 v109, 0, v109
	v_mul_f32_e32 v126, v126, v126
	v_mul_f32_e32 v127, v127, v127
	v_mul_f32_e32 v165, v106, v106
	v_cvt_pk_bf16_f32 v106, v126, v127
	v_pk_add_f32 v[120:121], v[120:121], v[144:145]
	v_pk_add_f32 v[116:117], v[116:117], v[140:141]
	v_pk_add_f32 v[114:115], v[114:115], v[138:139]
	v_max_f32_e32 v112, 0, v112
	v_max_f32_e32 v113, 0, v113
	v_max_f32_e32 v118, 0, v118
	v_max_f32_e32 v119, 0, v119
	v_mul_f32_e32 v122, v122, v122
	v_mul_f32_e32 v123, v123, v123
	v_mul_f32_e32 v128, v128, v128
	v_mul_f32_e32 v124, v124, v124
	v_mul_f32_e32 v129, v129, v129
	v_mul_f32_e32 v125, v125, v125
	v_mul_f32_e32 v110, v110, v110
	v_mul_f32_e32 v111, v111, v111
	v_mul_f32_e32 v171, v107, v107
	v_mul_f32_e32 v174, v108, v108
	v_mul_f32_e32 v175, v109, v109
	v_cvt_pk_bf16_f32 v107, v128, v129
	v_cvt_pk_bf16_f32 v108, v122, v123
	v_cvt_pk_bf16_f32 v109, v124, v125
	global_store_dwordx4 v[162:163], v[106:109], off
	v_pk_add_f32 v[98:99], v[98:99], v[130:131]
	v_max_f32_e32 v114, 0, v114
	v_cvt_pk_bf16_f32 v106, v110, v111
	v_max_f32_e32 v115, 0, v115
	v_max_f32_e32 v120, 0, v120
	v_max_f32_e32 v116, 0, v116
	v_max_f32_e32 v121, 0, v121
	v_max_f32_e32 v117, 0, v117
	v_mul_f32_e32 v112, v112, v112
	v_mul_f32_e32 v113, v113, v113
	v_mul_f32_e32 v118, v118, v118
	v_mul_f32_e32 v119, v119, v119
	v_cvt_pk_bf16_f32 v107, v112, v113
	v_cvt_pk_bf16_f32 v108, v165, v171
	v_cvt_pk_bf16_f32 v109, v174, v175
	global_store_dwordx4 v[162:163], v[106:109], off offset:256
	v_pk_add_f32 v[102:103], v[102:103], v[134:135]
	v_pk_add_f32 v[100:101], v[100:101], v[132:133]
	v_cvt_pk_bf16_f32 v106, v118, v119
	v_max_f32_e32 v98, 0, v98
	v_mul_f32_e32 v114, v114, v114
	v_mul_f32_e32 v115, v115, v115
	v_mul_f32_e32 v120, v120, v120
	v_mul_f32_e32 v116, v116, v116
	v_mul_f32_e32 v121, v121, v121
	v_mul_f32_e32 v117, v117, v117
	v_cvt_pk_bf16_f32 v107, v120, v121
	v_cvt_pk_bf16_f32 v108, v114, v115
	v_cvt_pk_bf16_f32 v109, v116, v117
	global_store_dwordx4 v[172:173], v[106:109], off
	v_pk_add_f32 v[104:105], v[104:105], v[136:137]
	v_max_f32_e32 v99, 0, v99
	v_mul_f32_e32 v106, v98, v98
	v_max_f32_e32 v98, 0, v103
	v_max_f32_e32 v100, 0, v100
	v_max_f32_e32 v102, 0, v102
	v_mul_f32_e32 v98, v98, v98
	v_mul_f32_e32 v103, v99, v99
	v_max_f32_e32 v99, 0, v104
	v_mul_f32_e32 v104, v100, v100
	v_max_f32_e32 v100, 0, v105
	v_max_f32_e32 v101, 0, v101
	v_mul_f32_e32 v102, v102, v102
	v_mul_f32_e32 v99, v99, v99
	v_mul_f32_e32 v100, v100, v100
	v_mul_f32_e32 v101, v101, v101
	v_cvt_pk_bf16_f32 v98, v102, v98
	v_cvt_pk_bf16_f32 v99, v99, v100
	v_cvt_pk_bf16_f32 v100, v106, v103
	v_cvt_pk_bf16_f32 v101, v104, v101
	global_store_dwordx4 v[172:173], v[98:101], off offset:256
	v_pk_add_f32 v[90:91], v[90:91], v[138:139]
	v_pk_add_f32 v[94:95], v[94:95], v[142:143]
	v_or_b32_e32 v98, 32, v164
	v_ashrrev_i32_e32 v99, 31, v98
	v_pk_add_f32 v[92:93], v[92:93], v[140:141]
	v_max_f32_e32 v90, 0, v90
	v_lshlrev_b64 v[98:99], 13, v[98:99]
	v_pk_add_f32 v[96:97], v[96:97], v[144:145]
	v_mul_f32_e32 v100, v90, v90
	v_max_f32_e32 v90, 0, v95
	v_max_f32_e32 v91, 0, v91
	v_max_f32_e32 v92, 0, v92
	v_lshl_add_u64 v[98:99], s[68:69], 0, v[98:99]
	v_max_f32_e32 v94, 0, v94
	v_mul_f32_e32 v90, v90, v90
	v_mul_f32_e32 v95, v91, v91
	v_max_f32_e32 v91, 0, v96
	v_mul_f32_e32 v96, v92, v92
	v_max_f32_e32 v92, 0, v97
	v_max_f32_e32 v93, 0, v93
	v_pk_add_f32 v[82:83], v[82:83], v[130:131]
	v_lshl_add_u64 v[98:99], v[98:99], 0, v[176:177]
	v_mul_f32_e32 v94, v94, v94
	v_mul_f32_e32 v91, v91, v91
	v_mul_f32_e32 v92, v92, v92
	v_mul_f32_e32 v93, v93, v93
	v_cvt_pk_bf16_f32 v90, v94, v90
	v_pk_add_f32 v[86:87], v[86:87], v[134:135]
	v_pk_add_f32 v[84:85], v[84:85], v[132:133]
	v_max_f32_e32 v82, 0, v82
	v_cvt_pk_bf16_f32 v91, v91, v92
	v_cvt_pk_bf16_f32 v92, v100, v95
	v_cvt_pk_bf16_f32 v93, v96, v93
	global_store_dwordx4 v[98:99], v[90:93], off
	v_pk_add_f32 v[88:89], v[88:89], v[136:137]
	v_max_f32_e32 v83, 0, v83
	v_mul_f32_e32 v90, v82, v82
	v_max_f32_e32 v82, 0, v87
	v_max_f32_e32 v84, 0, v84
	v_max_f32_e32 v86, 0, v86
	v_mul_f32_e32 v82, v82, v82
	v_mul_f32_e32 v87, v83, v83
	v_max_f32_e32 v83, 0, v88
	v_mul_f32_e32 v88, v84, v84
	v_max_f32_e32 v84, 0, v89
	v_max_f32_e32 v85, 0, v85
	v_mul_f32_e32 v86, v86, v86
	v_mul_f32_e32 v83, v83, v83
	v_mul_f32_e32 v84, v84, v84
	v_mul_f32_e32 v85, v85, v85
	v_cvt_pk_bf16_f32 v82, v86, v82
	v_cvt_pk_bf16_f32 v83, v83, v84
	v_cvt_pk_bf16_f32 v84, v90, v87
	v_cvt_pk_bf16_f32 v85, v88, v85
	global_store_dwordx4 v[98:99], v[82:85], off offset:256
	v_pk_add_f32 v[74:75], v[74:75], v[138:139]
	v_pk_add_f32 v[78:79], v[78:79], v[142:143]
	v_or_b32_e32 v82, 48, v164
	v_ashrrev_i32_e32 v83, 31, v82
	v_pk_add_f32 v[76:77], v[76:77], v[140:141]
	v_max_f32_e32 v74, 0, v74
	v_lshlrev_b64 v[82:83], 13, v[82:83]
	v_pk_add_f32 v[80:81], v[80:81], v[144:145]
	v_mul_f32_e32 v84, v74, v74
	v_max_f32_e32 v74, 0, v79
	v_max_f32_e32 v75, 0, v75
	v_max_f32_e32 v76, 0, v76
	v_lshl_add_u64 v[82:83], s[68:69], 0, v[82:83]
	v_max_f32_e32 v78, 0, v78
	v_mul_f32_e32 v74, v74, v74
	v_mul_f32_e32 v79, v75, v75
	v_max_f32_e32 v75, 0, v80
	v_mul_f32_e32 v80, v76, v76
	v_max_f32_e32 v76, 0, v81
	v_max_f32_e32 v77, 0, v77
	v_pk_add_f32 v[68:69], v[68:69], v[132:133]
	v_pk_add_f32 v[66:67], v[66:67], v[130:131]
	v_lshl_add_u64 v[82:83], v[82:83], 0, v[176:177]
	v_mul_f32_e32 v78, v78, v78
	v_mul_f32_e32 v75, v75, v75
	v_mul_f32_e32 v76, v76, v76
	v_mul_f32_e32 v77, v77, v77
	v_cvt_pk_bf16_f32 v74, v78, v74
	v_pk_add_f32 v[72:73], v[72:73], v[136:137]
	v_pk_add_f32 v[70:71], v[70:71], v[134:135]
	v_max_f32_e32 v66, 0, v66
	v_max_f32_e32 v67, 0, v67
	v_max_f32_e32 v68, 0, v68
	v_cvt_pk_bf16_f32 v75, v75, v76
	v_cvt_pk_bf16_f32 v76, v84, v79
	v_cvt_pk_bf16_f32 v77, v80, v77
	global_store_dwordx4 v[82:83], v[74:77], off
	v_max_f32_e32 v70, 0, v70
	v_max_f32_e32 v69, 0, v69
	v_mul_f32_e32 v74, v66, v66
	v_max_f32_e32 v66, 0, v71
	v_mul_f32_e32 v71, v67, v67
	v_max_f32_e32 v67, 0, v72
	v_mul_f32_e32 v72, v68, v68
	v_max_f32_e32 v68, 0, v73
	v_mul_f32_e32 v66, v66, v66
	v_mul_f32_e32 v67, v67, v67
	v_mul_f32_e32 v68, v68, v68
	v_pk_add_f32 v[58:59], v[58:59], v[138:139]
	v_mul_f32_e32 v70, v70, v70
	v_mul_f32_e32 v69, v69, v69
	v_cvt_pk_bf16_f32 v66, v70, v66
	v_cvt_pk_bf16_f32 v67, v67, v68
	v_cvt_pk_bf16_f32 v68, v74, v71
	v_pk_add_f32 v[62:63], v[62:63], v[142:143]
	v_pk_add_f32 v[60:61], v[60:61], v[140:141]
	v_max_f32_e32 v58, 0, v58
	v_cvt_pk_bf16_f32 v69, v72, v69
	global_store_dwordx4 v[82:83], v[66:69], off offset:256
	v_pk_add_f32 v[64:65], v[64:65], v[144:145]
	v_max_f32_e32 v62, 0, v62
	v_mul_f32_e32 v68, v58, v58
	v_max_f32_e32 v58, 0, v63
	v_max_f32_e32 v59, 0, v59
	v_max_f32_e32 v60, 0, v60
	v_mul_f32_e32 v62, v62, v62
	v_mul_f32_e32 v58, v58, v58
	v_mul_f32_e32 v63, v59, v59
	v_max_f32_e32 v59, 0, v64
	v_mul_f32_e32 v64, v60, v60
	v_max_f32_e32 v60, 0, v65
	v_mul_f32_e32 v59, v59, v59
	v_max_f32_e32 v61, 0, v61
	v_mul_f32_e32 v60, v60, v60
	v_cvt_pk_bf16_f32 v58, v62, v58
	v_add_co_u32_e32 v62, vcc, s73, v162
	v_pk_add_f32 v[52:53], v[52:53], v[132:133]
	v_pk_add_f32 v[50:51], v[50:51], v[130:131]
	v_mul_f32_e32 v61, v61, v61
	v_cvt_pk_bf16_f32 v59, v59, v60
	v_cvt_pk_bf16_f32 v60, v68, v63
	v_addc_co_u32_e32 v63, vcc, 0, v163, vcc
	v_pk_add_f32 v[56:57], v[56:57], v[136:137]
	v_pk_add_f32 v[54:55], v[54:55], v[134:135]
	v_max_f32_e32 v50, 0, v50
	v_max_f32_e32 v51, 0, v51
	v_max_f32_e32 v52, 0, v52
	v_cvt_pk_bf16_f32 v61, v64, v61
	global_store_dwordx4 v[62:63], v[58:61], off
	v_max_f32_e32 v54, 0, v54
	v_max_f32_e32 v53, 0, v53
	v_mul_f32_e32 v58, v50, v50
	v_max_f32_e32 v50, 0, v55
	v_mul_f32_e32 v55, v51, v51
	v_max_f32_e32 v51, 0, v56
	v_mul_f32_e32 v56, v52, v52
	v_max_f32_e32 v52, 0, v57
	v_mul_f32_e32 v50, v50, v50
	v_mul_f32_e32 v51, v51, v51
	v_mul_f32_e32 v52, v52, v52
	v_pk_add_f32 v[42:43], v[42:43], v[138:139]
	v_lshl_add_u64 v[66:67], v[162:163], 0, s[20:21]
	v_mul_f32_e32 v54, v54, v54
	v_mul_f32_e32 v53, v53, v53
	v_cvt_pk_bf16_f32 v50, v54, v50
	v_cvt_pk_bf16_f32 v51, v51, v52
	v_cvt_pk_bf16_f32 v52, v58, v55
	v_pk_add_f32 v[46:47], v[46:47], v[142:143]
	v_pk_add_f32 v[44:45], v[44:45], v[140:141]
	v_max_f32_e32 v42, 0, v42
	v_cvt_pk_bf16_f32 v53, v56, v53
	global_store_dwordx4 v[66:67], v[50:53], off offset:256
	v_pk_add_f32 v[48:49], v[48:49], v[144:145]
	v_max_f32_e32 v46, 0, v46
	v_mul_f32_e32 v52, v42, v42
	v_max_f32_e32 v42, 0, v47
	v_max_f32_e32 v43, 0, v43
	v_max_f32_e32 v44, 0, v44
	v_mul_f32_e32 v46, v46, v46
	v_mul_f32_e32 v42, v42, v42
	v_mul_f32_e32 v47, v43, v43
	v_max_f32_e32 v43, 0, v48
	v_mul_f32_e32 v48, v44, v44
	v_max_f32_e32 v44, 0, v49
	v_mul_f32_e32 v43, v43, v43
	v_max_f32_e32 v45, 0, v45
	v_mul_f32_e32 v44, v44, v44
	v_cvt_pk_bf16_f32 v42, v46, v42
	v_add_co_u32_e32 v46, vcc, s74, v162
	v_pk_add_f32 v[36:37], v[36:37], v[132:133]
	v_pk_add_f32 v[34:35], v[34:35], v[130:131]
	v_mul_f32_e32 v45, v45, v45
	v_cvt_pk_bf16_f32 v43, v43, v44
	v_cvt_pk_bf16_f32 v44, v52, v47
	v_addc_co_u32_e32 v47, vcc, 0, v163, vcc
	v_pk_add_f32 v[40:41], v[40:41], v[136:137]
	v_pk_add_f32 v[38:39], v[38:39], v[134:135]
	v_max_f32_e32 v34, 0, v34
	v_max_f32_e32 v35, 0, v35
	v_max_f32_e32 v36, 0, v36
	v_cvt_pk_bf16_f32 v45, v48, v45
	global_store_dwordx4 v[46:47], v[42:45], off
	v_max_f32_e32 v38, 0, v38
	v_max_f32_e32 v37, 0, v37
	v_mul_f32_e32 v42, v34, v34
	v_max_f32_e32 v34, 0, v39
	v_mul_f32_e32 v39, v35, v35
	v_max_f32_e32 v35, 0, v40
	v_mul_f32_e32 v40, v36, v36
	v_max_f32_e32 v36, 0, v41
	v_mul_f32_e32 v34, v34, v34
	v_mul_f32_e32 v35, v35, v35
	v_mul_f32_e32 v36, v36, v36
	v_pk_add_f32 v[26:27], v[26:27], v[138:139]
	v_lshl_add_u64 v[50:51], v[162:163], 0, s[22:23]
	v_mul_f32_e32 v38, v38, v38
	v_mul_f32_e32 v37, v37, v37
	v_cvt_pk_bf16_f32 v34, v38, v34
	v_cvt_pk_bf16_f32 v35, v35, v36
	v_cvt_pk_bf16_f32 v36, v42, v39
	v_pk_add_f32 v[30:31], v[30:31], v[142:143]
	v_pk_add_f32 v[28:29], v[28:29], v[140:141]
	v_max_f32_e32 v26, 0, v26
	v_cvt_pk_bf16_f32 v37, v40, v37
	global_store_dwordx4 v[50:51], v[34:37], off offset:256
	v_pk_add_f32 v[32:33], v[32:33], v[144:145]
	v_max_f32_e32 v30, 0, v30
	v_mul_f32_e32 v36, v26, v26
	v_max_f32_e32 v26, 0, v31
	v_max_f32_e32 v27, 0, v27
	v_max_f32_e32 v28, 0, v28
	v_mul_f32_e32 v30, v30, v30
	v_mul_f32_e32 v26, v26, v26
	v_mul_f32_e32 v31, v27, v27
	v_max_f32_e32 v27, 0, v32
	v_mul_f32_e32 v32, v28, v28
	v_max_f32_e32 v28, 0, v33
	v_mul_f32_e32 v27, v27, v27
	v_max_f32_e32 v29, 0, v29
	v_mul_f32_e32 v28, v28, v28
	v_cvt_pk_bf16_f32 v26, v30, v26
	v_add_co_u32_e32 v30, vcc, s75, v162
	v_pk_add_f32 v[20:21], v[20:21], v[132:133]
	v_pk_add_f32 v[18:19], v[18:19], v[130:131]
	v_mul_f32_e32 v29, v29, v29
	v_cvt_pk_bf16_f32 v27, v27, v28
	v_cvt_pk_bf16_f32 v28, v36, v31
	v_addc_co_u32_e32 v31, vcc, 0, v163, vcc
	v_pk_add_f32 v[24:25], v[24:25], v[136:137]
	v_pk_add_f32 v[22:23], v[22:23], v[134:135]
	v_max_f32_e32 v18, 0, v18
	v_max_f32_e32 v19, 0, v19
	v_max_f32_e32 v20, 0, v20
	v_cvt_pk_bf16_f32 v29, v32, v29
	global_store_dwordx4 v[30:31], v[26:29], off
	v_max_f32_e32 v22, 0, v22
	v_max_f32_e32 v21, 0, v21
	v_mul_f32_e32 v26, v18, v18
	v_max_f32_e32 v18, 0, v23
	v_mul_f32_e32 v23, v19, v19
	v_max_f32_e32 v19, 0, v24
	v_mul_f32_e32 v24, v20, v20
	v_max_f32_e32 v20, 0, v25
	v_mul_f32_e32 v18, v18, v18
	v_mul_f32_e32 v19, v19, v19
	v_mul_f32_e32 v20, v20, v20
	v_pk_add_f32 v[10:11], v[10:11], v[138:139]
	v_lshl_add_u64 v[34:35], v[162:163], 0, s[24:25]
	v_mul_f32_e32 v22, v22, v22
	v_mul_f32_e32 v21, v21, v21
	v_cvt_pk_bf16_f32 v18, v22, v18
	v_cvt_pk_bf16_f32 v19, v19, v20
	v_cvt_pk_bf16_f32 v20, v26, v23
	v_pk_add_f32 v[14:15], v[14:15], v[142:143]
	v_pk_add_f32 v[12:13], v[12:13], v[140:141]
	v_max_f32_e32 v10, 0, v10
	v_cvt_pk_bf16_f32 v21, v24, v21
	global_store_dwordx4 v[34:35], v[18:21], off offset:256
	v_pk_add_f32 v[16:17], v[16:17], v[144:145]
	v_max_f32_e32 v14, 0, v14
	v_mul_f32_e32 v20, v10, v10
	v_max_f32_e32 v10, 0, v15
	v_max_f32_e32 v11, 0, v11
	v_max_f32_e32 v12, 0, v12
	v_mul_f32_e32 v14, v14, v14
	v_mul_f32_e32 v10, v10, v10
	v_mul_f32_e32 v15, v11, v11
	v_max_f32_e32 v11, 0, v16
	v_mul_f32_e32 v16, v12, v12
	v_max_f32_e32 v12, 0, v17
	v_mul_f32_e32 v11, v11, v11
	v_max_f32_e32 v13, 0, v13
	v_mul_f32_e32 v12, v12, v12
	v_cvt_pk_bf16_f32 v10, v14, v10
	v_add_co_u32_e32 v14, vcc, s76, v162
	v_pk_add_f32 v[4:5], v[4:5], v[132:133]
	v_pk_add_f32 v[2:3], v[2:3], v[130:131]
	v_mul_f32_e32 v13, v13, v13
	v_cvt_pk_bf16_f32 v11, v11, v12
	v_cvt_pk_bf16_f32 v12, v20, v15
	v_addc_co_u32_e32 v15, vcc, 0, v163, vcc
	v_pk_add_f32 v[8:9], v[8:9], v[136:137]
	v_pk_add_f32 v[6:7], v[6:7], v[134:135]
	v_max_f32_e32 v2, 0, v2
	v_max_f32_e32 v3, 0, v3
	v_max_f32_e32 v4, 0, v4
	v_cvt_pk_bf16_f32 v13, v16, v13
	global_store_dwordx4 v[14:15], v[10:13], off
	v_max_f32_e32 v5, 0, v5
	v_lshl_add_u64 v[18:19], v[162:163], 0, s[26:27]
	v_mul_f32_e32 v10, v2, v2
	v_max_f32_e32 v2, 0, v7
	v_mul_f32_e32 v7, v3, v3
	v_max_f32_e32 v3, 0, v8
	v_mul_f32_e32 v8, v4, v4
	v_max_f32_e32 v4, 0, v9
	v_max_f32_e32 v6, 0, v6
	v_mul_f32_e32 v2, v2, v2
	v_mul_f32_e32 v3, v3, v3
	v_mul_f32_e32 v4, v4, v4
	v_mul_f32_e32 v5, v5, v5
	s_andn2_b64 vcc, exec, s[6:7]
	v_mul_f32_e32 v6, v6, v6
	v_cvt_pk_bf16_f32 v2, v6, v2
	v_cvt_pk_bf16_f32 v3, v3, v4
	v_cvt_pk_bf16_f32 v4, v10, v7
	v_cvt_pk_bf16_f32 v5, v8, v5
	global_store_dwordx4 v[18:19], v[2:5], off offset:256
	s_cbranch_vccnz .LBB0_577
	s_andn2_b64 vcc, exec, s[14:15]
	s_cbranch_vccnz .LBB0_576
	s_barrier
	s_branch .LBB0_576
